# v17 + batched rstd-cache miss path in FFN-up epilogue (2 load round trips instead of 8)
# speedup vs baseline: 1.0068x; 1.0027x over previous
.LBB0_595:
	v_mov_b32_e32 v134, s34
	ds_read_b32 v134, v134 offset:512
	v_lshl_add_u32 v170, s18, 8, v17
	v_or_b32_e32 v164, 16, v170
	v_or_b32_e32 v158, 32, v170
	v_or_b32_e32 v154, 48, v170
	s_waitcnt lgkmcnt(0)
	v_readfirstlane_b32 s16, v134
	s_mov_b64 s[4:5], -1
	v_ashrrev_i32_e32 v171, 31, v170
	s_cmp_lg_u32 s16, s18
	v_ashrrev_i32_e32 v165, 31, v164
	v_ashrrev_i32_e32 v159, 31, v158
	v_ashrrev_i32_e32 v155, 31, v154
	v_add_u32_e32 v172, 0x80, v170
	s_cbranch_scc0 .LBB0_601
	v_lshlrev_b64 v[134:135], 7, v[170:171]
	s_mov_b64 s[4:5], 0x1000
	v_lshl_add_u64 v[134:135], v[146:147], 0, v[134:135]
	v_add_u32_e32 v152, 0x80, v170
	v_lshl_add_u64 v[136:137], v[134:135], 0, s[4:5]
	v_ashrrev_i32_e32 v153, 31, v152
	global_load_dwordx4 v[190:193], v[134:135], off
	global_load_dwordx4 v[194:197], v[134:135], off offset:16
	global_load_dwordx4 v[204:207], v[134:135], off offset:2048
	global_load_dwordx4 v[208:211], v[134:135], off offset:2064
	global_load_dwordx4 v[212:215], v[136:137], off
	global_load_dwordx4 v[216:219], v[136:137], off offset:16
	global_load_dwordx4 v[220:223], v[136:137], off offset:2048
	global_load_dwordx4 v[224:227], v[136:137], off offset:2064
	s_mov_b64 s[4:5], 0x4000
	v_lshl_add_u64 v[138:139], v[134:135], 0, s[4:5]
	s_mov_b64 s[4:5], 0x5000
	v_lshl_add_u64 v[140:141], v[134:135], 0, s[4:5]
	s_mov_b32 s40, 0x3a000000
	s_mov_b32 s16, 0x800000
	v_mov_b32_e32 v176, 0x358637bd
	s_waitcnt vmcnt(0)
	v_add_f32_e32 v174, v190, v191
	v_add_f32_e32 v168, v204, v205
	v_add_f32_e32 v166, v212, v213
	v_add_f32_e32 v162, v220, v221
	v_add_f32_e32 v174, v174, v192
	v_add_f32_e32 v168, v168, v206
	v_add_f32_e32 v166, v166, v214
	v_add_f32_e32 v162, v162, v222
	v_add_f32_e32 v174, v174, v193
	v_add_f32_e32 v168, v168, v207
	v_add_f32_e32 v166, v166, v215
	v_add_f32_e32 v162, v162, v223
	v_add_f32_e32 v174, v174, v194
	v_add_f32_e32 v168, v168, v208
	v_add_f32_e32 v166, v166, v216
	v_add_f32_e32 v162, v162, v224
	v_add_f32_e32 v174, v174, v195
	v_add_f32_e32 v168, v168, v209
	v_add_f32_e32 v166, v166, v217
	v_add_f32_e32 v162, v162, v225
	v_add_f32_e32 v174, v174, v196
	v_add_f32_e32 v168, v168, v210
	v_add_f32_e32 v166, v166, v218
	v_add_f32_e32 v162, v162, v226
	v_add_f32_e32 v174, v174, v197
	v_add_f32_e32 v168, v168, v211
	v_add_f32_e32 v166, v166, v219
	v_add_f32_e32 v162, v162, v227
	global_load_dwordx4 v[190:193], v[138:139], off
	global_load_dwordx4 v[194:197], v[138:139], off offset:16
	global_load_dwordx4 v[204:207], v[138:139], off offset:2048
	global_load_dwordx4 v[208:211], v[138:139], off offset:2064
	global_load_dwordx4 v[212:215], v[140:141], off
	global_load_dwordx4 v[216:219], v[140:141], off offset:16
	global_load_dwordx4 v[220:223], v[140:141], off offset:2048
	global_load_dwordx4 v[224:227], v[140:141], off offset:2064
	s_waitcnt vmcnt(0)
	v_add_f32_e32 v160, v190, v191
	v_add_f32_e32 v156, v204, v205
	v_add_f32_e32 v140, v212, v213
	v_add_f32_e32 v134, v220, v221
	v_add_f32_e32 v160, v160, v192
	v_add_f32_e32 v156, v156, v206
	v_add_f32_e32 v140, v140, v214
	v_add_f32_e32 v134, v134, v222
	v_add_f32_e32 v160, v160, v193
	v_add_f32_e32 v156, v156, v207
	v_add_f32_e32 v140, v140, v215
	v_add_f32_e32 v134, v134, v223
	v_add_f32_e32 v160, v160, v194
	v_add_f32_e32 v156, v156, v208
	v_add_f32_e32 v140, v140, v216
	v_add_f32_e32 v134, v134, v224
	v_add_f32_e32 v160, v160, v195
	v_add_f32_e32 v156, v156, v209
	v_add_f32_e32 v140, v140, v217
	v_add_f32_e32 v134, v134, v225
	v_add_f32_e32 v160, v160, v196
	v_add_f32_e32 v156, v156, v210
	v_add_f32_e32 v140, v140, v218
	v_add_f32_e32 v134, v134, v226
	v_add_f32_e32 v160, v160, v197
	v_add_f32_e32 v156, v156, v211
	v_add_f32_e32 v140, v140, v219
	v_add_f32_e32 v134, v134, v227
	ds_bpermute_b32 v190, v163, v174
	ds_bpermute_b32 v191, v163, v168
	ds_bpermute_b32 v192, v163, v166
	ds_bpermute_b32 v193, v163, v162
	ds_bpermute_b32 v194, v163, v160
	ds_bpermute_b32 v195, v163, v156
	ds_bpermute_b32 v196, v163, v140
	ds_bpermute_b32 v197, v163, v134
	s_waitcnt lgkmcnt(0)
	v_add_f32_e32 v174, v174, v190
	v_add_f32_e32 v168, v168, v191
	v_add_f32_e32 v166, v166, v192
	v_add_f32_e32 v162, v162, v193
	v_add_f32_e32 v160, v160, v194
	v_add_f32_e32 v156, v156, v195
	v_add_f32_e32 v140, v140, v196
	v_add_f32_e32 v134, v134, v197
	ds_bpermute_b32 v190, v169, v174
	ds_bpermute_b32 v191, v169, v168
	ds_bpermute_b32 v192, v169, v166
	ds_bpermute_b32 v193, v169, v162
	ds_bpermute_b32 v194, v169, v160
	ds_bpermute_b32 v195, v169, v156
	ds_bpermute_b32 v196, v169, v140
	ds_bpermute_b32 v197, v169, v134
	s_waitcnt lgkmcnt(0)
	v_add_f32_e32 v174, v174, v190
	v_add_f32_e32 v168, v168, v191
	v_add_f32_e32 v166, v166, v192
	v_add_f32_e32 v162, v162, v193
	v_add_f32_e32 v160, v160, v194
	v_add_f32_e32 v156, v156, v195
	v_add_f32_e32 v140, v140, v196
	v_add_f32_e32 v134, v134, v197
	v_fma_f32 v174, v174, s40, v176
	v_mul_f32_e32 v190, 0x4b800000, v174
	v_cmp_gt_f32_e32 vcc, s16, v174
	s_nop 1
	v_cndmask_b32_e32 v174, v174, v190, vcc
	v_rsq_f32_e32 v174, v174
	s_nop 0
	v_mul_f32_e32 v190, 0x45800000, v174
	v_cndmask_b32_e32 v174, v174, v190, vcc
	v_fma_f32 v168, v168, s40, v176
	v_mul_f32_e32 v190, 0x4b800000, v168
	v_cmp_gt_f32_e32 vcc, s16, v168
	s_nop 1
	v_cndmask_b32_e32 v168, v168, v190, vcc
	v_rsq_f32_e32 v168, v168
	s_nop 0
	v_mul_f32_e32 v190, 0x45800000, v168
	v_cndmask_b32_e32 v168, v168, v190, vcc
	v_fma_f32 v166, v166, s40, v176
	v_mul_f32_e32 v190, 0x4b800000, v166
	v_cmp_gt_f32_e32 vcc, s16, v166
	s_nop 1
	v_cndmask_b32_e32 v166, v166, v190, vcc
	v_rsq_f32_e32 v166, v166
	s_nop 0
	v_mul_f32_e32 v190, 0x45800000, v166
	v_cndmask_b32_e32 v166, v166, v190, vcc
	v_fma_f32 v162, v162, s40, v176
	v_mul_f32_e32 v190, 0x4b800000, v162
	v_cmp_gt_f32_e32 vcc, s16, v162
	s_nop 1
	v_cndmask_b32_e32 v162, v162, v190, vcc
	v_rsq_f32_e32 v162, v162
	s_nop 0
	v_mul_f32_e32 v190, 0x45800000, v162
	v_cndmask_b32_e32 v162, v162, v190, vcc
	v_fma_f32 v160, v160, s40, v176
	v_mul_f32_e32 v190, 0x4b800000, v160
	v_cmp_gt_f32_e32 vcc, s16, v160
	s_nop 1
	v_cndmask_b32_e32 v160, v160, v190, vcc
	v_rsq_f32_e32 v160, v160
	s_nop 0
	v_mul_f32_e32 v190, 0x45800000, v160
	v_cndmask_b32_e32 v160, v160, v190, vcc
	v_fma_f32 v156, v156, s40, v176
	v_mul_f32_e32 v190, 0x4b800000, v156
	v_cmp_gt_f32_e32 vcc, s16, v156
	s_nop 1
	v_cndmask_b32_e32 v156, v156, v190, vcc
	v_rsq_f32_e32 v156, v156
	s_nop 0
	v_mul_f32_e32 v190, 0x45800000, v156
	v_cndmask_b32_e32 v156, v156, v190, vcc
	v_fma_f32 v140, v140, s40, v176
	v_mul_f32_e32 v190, 0x4b800000, v140
	v_cmp_gt_f32_e32 vcc, s16, v140
	s_nop 1
	v_cndmask_b32_e32 v140, v140, v190, vcc
	v_rsq_f32_e32 v140, v140
	s_nop 0
	v_mul_f32_e32 v190, 0x45800000, v140
	v_cndmask_b32_e32 v140, v140, v190, vcc
	v_fma_f32 v134, v134, s40, v176
	v_mul_f32_e32 v190, 0x4b800000, v134
	v_cmp_gt_f32_e32 vcc, s16, v134
	s_nop 1
	v_cndmask_b32_e32 v134, v134, v190, vcc
	v_rsq_f32_e32 v134, v134
	s_nop 0
	v_mul_f32_e32 v190, 0x45800000, v134
	v_cndmask_b32_e32 v134, v134, v190, vcc
	s_and_saveexec_b64 s[4:5], s[2:3]
	s_xor_b64 s[4:5], exec, s[4:5]
	s_andn2_saveexec_b64 s[4:5], s[4:5]
	s_cbranch_execz .LBB0_598
	ds_write2_b32 v182, v174, v168 offset1:16
	ds_write2_b32 v182, v166, v162 offset0:32 offset1:48
	ds_write2_b32 v182, v160, v156 offset0:64 offset1:80
	ds_write2_b32 v182, v140, v134 offset0:96 offset1:112
